# post_tile: 8-lane exchanges via DPP moves instead of ds_bpermute round trips
# speedup vs baseline: 1.0037x; 1.0022x over previous
.LBB0_293:
	s_andn2_saveexec_b64 s[2:3], s[2:3]
	v_mov_b32_e32 v30, v26
	s_or_b64 exec, exec, s[2:3]
	v_add_u32_e32 v28, s12, v27
	v_mov_b64_e32 v[54:55], s[10:11]
	v_mad_i64_i32 v[54:55], s[2:3], v28, s23, v[54:55]
	v_ashrrev_i32_e32 v31, 31, v30
	v_lshl_add_u64 v[30:31], v[30:31], 1, v[54:55]
	v_lshl_add_u64 v[30:31], v[30:31], 0, v[0:1]
	global_load_dwordx4 v[82:85], v[30:31], off
	v_lshl_add_u32 v27, v27, 5, 0
	v_cmp_lt_i32_e64 s[50:51], 0, v62
	s_waitcnt vmcnt(0)
	v_and_b32_e32 v60, 0xffff0000, v82
	v_lshlrev_b32_e32 v29, 16, v82
	v_mul_f32_e32 v33, v60, v60
	v_lshlrev_b32_e32 v57, 16, v83
	v_fmac_f32_e32 v33, v29, v29
	v_and_b32_e32 v56, 0xffff0000, v83
	v_fmac_f32_e32 v33, v57, v57
	v_lshlrev_b32_e32 v54, 16, v84
	v_fmac_f32_e32 v33, v56, v56
	v_and_b32_e32 v55, 0xffff0000, v84
	v_and_b32_e32 v58, 0xffff0000, v85
	v_lshlrev_b32_e32 v59, 16, v85
	v_fmac_f32_e32 v33, v54, v54
	v_pk_mul_f32 v[30:31], v[58:59], v[58:59]
	v_fmac_f32_e32 v33, v55, v55
	v_add_f32_e32 v31, v31, v33
	v_add_f32_e32 v30, v30, v31
	s_nop 1
	v_mov_b32_dpp v31, v30 quad_perm:[1,0,3,2] row_mask:0xf bank_mask:0xf
	s_waitcnt lgkmcnt(0)
	v_add_f32_e32 v30, v30, v31
	s_nop 1
	v_mov_b32_dpp v31, v30 quad_perm:[2,3,0,1] row_mask:0xf bank_mask:0xf
	s_waitcnt lgkmcnt(0)
	v_add_f32_e32 v30, v30, v31
	s_nop 1
	v_mov_b32_dpp v31, v30 row_half_mirror row_mask:0xf bank_mask:0xf
	s_waitcnt lgkmcnt(0)
	v_add_f32_e32 v30, v30, v31
	v_fmamk_f32 v30, v30, 0x3c800000, v188
	v_mul_f32_e32 v31, 0x4f800000, v30
	v_cmp_gt_f32_e32 vcc, s66, v30
	s_nop 1
	v_cndmask_b32_e32 v30, v30, v31, vcc
	v_sqrt_f32_e32 v31, v30
	s_nop 0
	v_add_u32_e32 v33, -1, v31
	v_add_u32_e32 v61, 1, v31
	v_fma_f32 v82, -v33, v31, v30
	v_fma_f32 v83, -v61, v31, v30
	v_cmp_ge_f32_e64 s[48:49], 0, v82
	s_nop 1
	v_cndmask_b32_e64 v31, v31, v33, s[48:49]
	v_cmp_lt_f32_e64 s[48:49], 0, v83
	s_nop 1
	v_cndmask_b32_e64 v31, v31, v61, s[48:49]
	v_mul_f32_e32 v33, 0x37800000, v31
	v_cndmask_b32_e32 v31, v31, v33, vcc
	v_cmp_class_f32_e32 vcc, v30, v192
	v_cmp_gt_u32_e64 s[48:49], 10, v32
	s_nop 0
	v_cndmask_b32_e32 v30, v31, v30, vcc
	v_div_scale_f32 v31, s[2:3], v30, v30, 1.0
	v_rcp_f32_e32 v33, v31
	v_div_scale_f32 v61, vcc, 1.0, v30, 1.0
	v_cndmask_b32_e64 v82, v18, v10, s[48:49]
	v_fma_f32 v83, -v31, v33, 1.0
	v_fmac_f32_e32 v33, v83, v33
	v_mul_f32_e32 v83, v61, v33
	v_fma_f32 v84, -v31, v83, v61
	v_fmac_f32_e32 v83, v84, v33
	v_fma_f32 v31, -v31, v83, v61
	v_div_fmas_f32 v31, v31, v33, v83
	v_div_fixup_f32 v61, v31, v30, 1.0
	v_mul_f32_e32 v29, v61, v29
	v_cndmask_b32_e64 v30, v82, v2, s[44:45]
	v_mul_f32_e32 v30, v30, v29
	s_nop 1
	v_mov_b32_dpp v31, v30 quad_perm:[1,0,3,2] row_mask:0xf bank_mask:0xf
	v_cmp_lt_u32_e32 vcc, 9, v32
	ds_read2st64_b32 v[32:33], v27 offset1:8
	v_ashrrev_i32_e32 v29, 31, v28
	s_and_saveexec_b64 s[2:3], s[50:51]
	s_xor_b64 s[2:3], exec, s[2:3]
	s_cbranch_execz .LBB0_299
	v_cmp_eq_u32_e64 s[50:51], 1, v62
	s_and_saveexec_b64 s[8:9], s[50:51]
	s_cbranch_execz .LBB0_298
	s_waitcnt lgkmcnt(0)
	v_mov_b32_e32 v82, v33
	v_mov_b32_e32 v83, v32
	v_mov_b32_e32 v32, v31
	v_mov_b32_e32 v33, v30
	v_pk_mul_f32 v[30:31], v[82:83], v[32:33]
	s_nop 0
	v_add_f32_e32 v30, v30, v31

.LBB0_301:
	s_or_b64 exec, exec, s[2:3]
	s_waitcnt lgkmcnt(0)
	v_cndmask_b32_e64 v32, v19, v11, s[48:49]
	v_mul_f32_e32 v31, v61, v60
	v_cndmask_b32_e64 v32, v32, v3, s[44:45]
	v_cndmask_b32_e64 v33, v20, v12, s[48:49]
	v_mul_f32_e32 v31, v32, v31
	v_mul_f32_e32 v32, v61, v57
	v_cndmask_b32_e64 v33, v33, v4, s[44:45]
	v_mul_f32_e32 v32, v33, v32
	v_mul_f32_e32 v33, v61, v56
	v_cndmask_b32_e64 v56, v21, v13, s[48:49]
	v_cndmask_b32_e64 v56, v56, v5, s[44:45]
	v_mul_f32_e32 v33, v56, v33
	v_cndmask_b32_e64 v56, v22, v14, s[48:49]
	v_mul_f32_e32 v54, v61, v54
	v_cndmask_b32_e64 v56, v56, v6, s[44:45]
	v_mul_f32_e32 v54, v56, v54
	v_cndmask_b32_e64 v56, v23, v15, s[48:49]
	v_mul_f32_e32 v55, v61, v55
	v_cndmask_b32_e64 v56, v56, v7, s[44:45]
	v_cndmask_b32_e64 v57, v24, v16, s[48:49]
	v_mul_f32_e32 v55, v56, v55
	v_mul_f32_e32 v56, v61, v59
	v_cndmask_b32_e64 v57, v57, v8, s[44:45]
	v_mul_f32_e32 v56, v57, v56
	v_mul_f32_e32 v57, v61, v58
	v_cndmask_b32_e64 v58, v25, v17, s[48:49]
	v_cndmask_b32_e64 v58, v58, v9, s[44:45]
	v_mul_f32_e32 v57, v58, v57
	v_add_u32_e32 v58, 4, v27
	s_nop 1
	v_mov_b32_dpp v59, v31 quad_perm:[1,0,3,2] row_mask:0xf bank_mask:0xf
	ds_read2st64_b32 v[60:61], v58 offset1:8
	v_cmp_lt_i32_e64 s[48:49], 0, v62
	s_and_saveexec_b64 s[2:3], s[48:49]
	s_xor_b64 s[2:3], exec, s[2:3]
	s_cbranch_execz .LBB0_305
	v_cmp_eq_u32_e64 s[48:49], 1, v62
	s_and_saveexec_b64 s[8:9], s[48:49]
	s_cbranch_execz .LBB0_304
	v_mov_b32_e32 v58, v31
	s_waitcnt lgkmcnt(0)
	v_mul_f32_e32 v82, v31, v60
	v_pk_fma_f32 v[58:59], v[58:59], v[60:61], v[82:83] op_sel_hi:[1,1,0]
	s_nop 0
	v_mov_b32_e32 v31, v59

.LBB0_307:
	s_or_b64 exec, exec, s[2:3]
	v_add_u32_e32 v58, 8, v27
	s_waitcnt lgkmcnt(0)
	s_nop 1
	v_mov_b32_dpp v59, v32 quad_perm:[1,0,3,2] row_mask:0xf bank_mask:0xf
	s_waitcnt lgkmcnt(0)
	ds_read2st64_b32 v[60:61], v58 offset1:8
	v_cmp_lt_i32_e64 s[48:49], 0, v62
	s_and_saveexec_b64 s[2:3], s[48:49]
	s_xor_b64 s[2:3], exec, s[2:3]
	s_cbranch_execz .LBB0_311
	v_cmp_eq_u32_e64 s[48:49], 1, v62
	s_and_saveexec_b64 s[8:9], s[48:49]
	s_cbranch_execz .LBB0_310
	v_mov_b32_e32 v58, v32
	s_waitcnt lgkmcnt(0)
	v_mul_f32_e32 v32, v59, v61
	v_pk_fma_f32 v[58:59], v[58:59], v[60:61], v[32:33] op_sel_hi:[1,1,0]
	s_nop 0
	v_mov_b32_e32 v32, v58

.LBB0_313:
	s_or_b64 exec, exec, s[2:3]
	v_add_u32_e32 v58, 12, v27
	s_waitcnt lgkmcnt(0)
	s_nop 1
	v_mov_b32_dpp v59, v33 quad_perm:[1,0,3,2] row_mask:0xf bank_mask:0xf
	s_waitcnt lgkmcnt(0)
	ds_read2st64_b32 v[60:61], v58 offset1:8
	v_cmp_lt_i32_e64 s[48:49], 0, v62
	s_and_saveexec_b64 s[2:3], s[48:49]
	s_xor_b64 s[2:3], exec, s[2:3]
	s_cbranch_execz .LBB0_317
	v_cmp_eq_u32_e64 s[48:49], 1, v62
	s_and_saveexec_b64 s[8:9], s[48:49]
	s_cbranch_execz .LBB0_316
	v_mov_b32_e32 v58, v33
	s_waitcnt lgkmcnt(0)
	v_mul_f32_e32 v82, v59, v61
	v_pk_fma_f32 v[58:59], v[58:59], v[60:61], v[82:83] op_sel_hi:[1,1,0]
	s_nop 0
	v_mov_b32_e32 v33, v58

.LBB0_319:
	s_or_b64 exec, exec, s[2:3]
	v_add_u32_e32 v58, 16, v27
	s_waitcnt lgkmcnt(0)
	s_nop 1
	v_mov_b32_dpp v59, v54 quad_perm:[1,0,3,2] row_mask:0xf bank_mask:0xf
	s_waitcnt lgkmcnt(0)
	ds_read2st64_b32 v[60:61], v58 offset1:8
	v_cmp_lt_i32_e64 s[48:49], 0, v62
	s_and_saveexec_b64 s[2:3], s[48:49]
	s_xor_b64 s[2:3], exec, s[2:3]
	s_cbranch_execz .LBB0_323
	v_cmp_eq_u32_e64 s[48:49], 1, v62
	s_and_saveexec_b64 s[8:9], s[48:49]
	s_cbranch_execz .LBB0_322
	v_mov_b32_e32 v58, v54
	s_waitcnt lgkmcnt(0)
	v_mul_f32_e32 v54, v59, v61
	v_pk_fma_f32 v[58:59], v[58:59], v[60:61], v[54:55] op_sel_hi:[1,1,0]
	s_nop 0
	v_mov_b32_e32 v54, v58

.LBB0_325:
	s_or_b64 exec, exec, s[2:3]
	v_add_u32_e32 v58, 20, v27
	s_waitcnt lgkmcnt(0)
	s_nop 1
	v_mov_b32_dpp v59, v55 quad_perm:[1,0,3,2] row_mask:0xf bank_mask:0xf
	s_waitcnt lgkmcnt(0)
	ds_read2st64_b32 v[60:61], v58 offset1:8
	v_cmp_lt_i32_e64 s[48:49], 0, v62
	s_and_saveexec_b64 s[2:3], s[48:49]
	s_xor_b64 s[2:3], exec, s[2:3]
	s_cbranch_execz .LBB0_329
	v_cmp_eq_u32_e64 s[48:49], 1, v62
	s_and_saveexec_b64 s[8:9], s[48:49]
	s_cbranch_execz .LBB0_328
	v_mov_b32_e32 v58, v55
	s_waitcnt lgkmcnt(0)
	v_mul_f32_e32 v82, v59, v61
	v_pk_fma_f32 v[58:59], v[58:59], v[60:61], v[82:83] op_sel_hi:[1,1,0]
	s_nop 0
	v_mov_b32_e32 v55, v58

.LBB0_331:
	s_or_b64 exec, exec, s[2:3]
	v_add_u32_e32 v58, 24, v27
	s_waitcnt lgkmcnt(0)
	s_nop 1
	v_mov_b32_dpp v59, v56 quad_perm:[1,0,3,2] row_mask:0xf bank_mask:0xf
	s_waitcnt lgkmcnt(0)
	ds_read2st64_b32 v[60:61], v58 offset1:8
	v_cmp_lt_i32_e64 s[48:49], 0, v62
	s_and_saveexec_b64 s[2:3], s[48:49]
	s_xor_b64 s[2:3], exec, s[2:3]
	s_cbranch_execz .LBB0_335
	v_cmp_eq_u32_e64 s[48:49], 1, v62
	s_and_saveexec_b64 s[8:9], s[48:49]
	s_cbranch_execz .LBB0_334
	v_mov_b32_e32 v58, v56
	s_waitcnt lgkmcnt(0)
	v_mul_f32_e32 v56, v59, v61
	v_pk_fma_f32 v[58:59], v[58:59], v[60:61], v[56:57] op_sel_hi:[1,1,0]
	s_nop 0
	v_mov_b32_e32 v56, v58

.LBB0_337:
	s_or_b64 exec, exec, s[2:3]
	v_add_u32_e32 v27, 28, v27
	s_waitcnt lgkmcnt(0)
	s_nop 1
	v_mov_b32_dpp v59, v57 quad_perm:[1,0,3,2] row_mask:0xf bank_mask:0xf
	s_waitcnt lgkmcnt(0)
	ds_read2st64_b32 v[60:61], v27 offset1:8
	v_cmp_lt_i32_e64 s[48:49], 0, v62
	s_and_saveexec_b64 s[2:3], s[48:49]
	s_xor_b64 s[2:3], exec, s[2:3]
	s_cbranch_execz .LBB0_341
	v_cmp_eq_u32_e64 s[48:49], 1, v62
	s_and_saveexec_b64 s[8:9], s[48:49]
	s_cbranch_execz .LBB0_340
	v_mov_b32_e32 v58, v57
	s_waitcnt lgkmcnt(0)
	v_mul_f32_e32 v82, v59, v61
	v_pk_fma_f32 v[58:59], v[58:59], v[60:61], v[82:83] op_sel_hi:[1,1,0]
	s_nop 0
	v_mov_b32_e32 v57, v58

.LBB0_343:
	s_or_b64 exec, exec, s[2:3]
	s_and_saveexec_b64 s[2:3], s[46:47]
	s_xor_b64 s[2:3], exec, s[2:3]
	s_cbranch_execz .LBB0_349
	v_lshlrev_b64 v[28:29], 8, v[28:29]
	v_lshl_add_u64 v[28:29], s[86:87], 0, v[28:29]
	v_mov_b32_e32 v27, v1
	v_lshl_add_u64 v[26:27], v[26:27], 1, v[28:29]
	s_and_saveexec_b64 s[8:9], vcc
	s_xor_b64 s[8:9], exec, s[8:9]
	s_cbranch_execz .LBB0_346
	s_mov_b64 s[30:31], 0x13ffb00
	s_waitcnt lgkmcnt(0)
	v_lshl_add_u64 v[58:59], v[26:27], 0, s[30:31]
.LBB0_346:
	s_andn2_saveexec_b64 s[8:9], s[8:9]
	s_cbranch_execz .LBB0_348
	s_mov_b64 s[30:31], 0xfffc00
	s_waitcnt lgkmcnt(0)
	v_lshl_add_u64 v[58:59], v[26:27], 0, s[30:31]

.LBB0_350:
	v_lshlrev_b64 v[28:29], 10, v[28:29]
	v_lshl_add_u64 v[28:29], s[86:87], 0, v[28:29]
	v_ashrrev_i32_e32 v27, 31, v26
	s_waitcnt lgkmcnt(0)
	v_lshl_add_u64 v[58:59], v[26:27], 1, v[28:29]

.LBB0_357:
	s_andn2_saveexec_b64 s[2:3], s[2:3]
	v_mov_b32_e32 v30, v26
	s_or_b64 exec, exec, s[2:3]
	v_add_u32_e32 v28, s12, v27
	v_mov_b64_e32 v[54:55], s[10:11]
	v_mad_i64_i32 v[54:55], s[2:3], v28, s23, v[54:55]
	v_ashrrev_i32_e32 v31, 31, v30
	v_lshl_add_u64 v[30:31], v[30:31], 1, v[54:55]
	v_lshl_add_u64 v[30:31], v[30:31], 0, v[0:1]
	global_load_dwordx4 v[56:59], v[30:31], off
	v_lshl_add_u32 v27, v27, 5, 0
	v_cmp_lt_i32_e64 s[50:51], 0, v62
	s_waitcnt vmcnt(0)
	v_and_b32_e32 v82, 0xffff0000, v56
	v_lshlrev_b32_e32 v29, 16, v56
	v_mul_f32_e32 v32, v82, v82
	v_lshlrev_b32_e32 v61, 16, v57
	v_fmac_f32_e32 v32, v29, v29
	v_and_b32_e32 v60, 0xffff0000, v57
	v_fmac_f32_e32 v32, v61, v61
	v_lshlrev_b32_e32 v57, 16, v58
	v_fmac_f32_e32 v32, v60, v60
	v_and_b32_e32 v56, 0xffff0000, v58
	v_and_b32_e32 v58, 0xffff0000, v59
	v_lshlrev_b32_e32 v59, 16, v59
	v_fmac_f32_e32 v32, v57, v57
	v_pk_mul_f32 v[30:31], v[58:59], v[58:59]
	v_fmac_f32_e32 v32, v56, v56
	v_add_f32_e32 v31, v31, v32
	v_add_f32_e32 v30, v30, v31
	s_nop 1
	v_mov_b32_dpp v31, v30 quad_perm:[1,0,3,2] row_mask:0xf bank_mask:0xf
	s_waitcnt lgkmcnt(0)
	v_add_f32_e32 v30, v30, v31
	s_nop 1
	v_mov_b32_dpp v31, v30 quad_perm:[2,3,0,1] row_mask:0xf bank_mask:0xf
	s_waitcnt lgkmcnt(0)
	v_add_f32_e32 v30, v30, v31
	s_nop 1
	v_mov_b32_dpp v31, v30 row_half_mirror row_mask:0xf bank_mask:0xf
	s_waitcnt lgkmcnt(0)
	v_add_f32_e32 v30, v30, v31
	v_fmamk_f32 v30, v30, 0x3c800000, v188
	v_mul_f32_e32 v31, 0x4f800000, v30
	v_cmp_gt_f32_e32 vcc, s66, v30
	s_nop 1
	v_cndmask_b32_e32 v30, v30, v31, vcc
	v_sqrt_f32_e32 v31, v30
	s_nop 0
	v_add_u32_e32 v32, -1, v31
	v_add_u32_e32 v54, 1, v31
	v_fma_f32 v55, -v32, v31, v30
	v_fma_f32 v83, -v54, v31, v30
	v_cmp_ge_f32_e64 s[48:49], 0, v55
	s_nop 1
	v_cndmask_b32_e64 v31, v31, v32, s[48:49]
	v_cmp_lt_f32_e64 s[48:49], 0, v83
	s_nop 1
	v_cndmask_b32_e64 v31, v31, v54, s[48:49]
	v_mul_f32_e32 v32, 0x37800000, v31
	v_cndmask_b32_e32 v31, v31, v32, vcc
	v_cmp_class_f32_e32 vcc, v30, v192
	v_cmp_gt_u32_e64 s[48:49], 10, v33
	s_nop 0
	v_cndmask_b32_e32 v30, v31, v30, vcc
	v_div_scale_f32 v31, s[2:3], v30, v30, 1.0
	v_rcp_f32_e32 v32, v31
	v_div_scale_f32 v55, vcc, 1.0, v30, 1.0
	v_cndmask_b32_e64 v54, v18, v10, s[48:49]
	v_fma_f32 v83, -v31, v32, 1.0
	v_fmac_f32_e32 v32, v83, v32
	v_mul_f32_e32 v83, v55, v32
	v_fma_f32 v84, -v31, v83, v55
	v_fmac_f32_e32 v83, v84, v32
	v_fma_f32 v31, -v31, v83, v55
	v_div_fmas_f32 v31, v31, v32, v83
	v_div_fixup_f32 v83, v31, v30, 1.0
	v_mul_f32_e32 v29, v83, v29
	v_cndmask_b32_e64 v30, v54, v2, s[44:45]
	v_mul_f32_e32 v30, v30, v29
	s_nop 1
	v_mov_b32_dpp v32, v30 quad_perm:[1,0,3,2] row_mask:0xf bank_mask:0xf
	ds_read2st64_b32 v[54:55], v27 offset1:8
	v_ashrrev_i32_e32 v29, 31, v28
	v_cmp_lt_u32_e32 vcc, 9, v33
	s_and_saveexec_b64 s[2:3], s[50:51]
	s_xor_b64 s[2:3], exec, s[2:3]
	s_cbranch_execz .LBB0_363
	v_cmp_eq_u32_e64 s[50:51], 1, v62
	s_and_saveexec_b64 s[8:9], s[50:51]
	s_cbranch_execz .LBB0_362
	s_waitcnt lgkmcnt(0)
	v_mov_b32_e32 v84, v55
	v_mov_b32_e32 v85, v54
	v_mov_b32_e32 v33, v30
	v_pk_mul_f32 v[30:31], v[84:85], v[32:33]
	s_nop 0
	v_add_f32_e32 v30, v30, v31

.LBB0_363:
	s_andn2_saveexec_b64 s[2:3], s[2:3]
	s_cbranch_execz .LBB0_365
	s_waitcnt lgkmcnt(0)
	v_mov_b32_e32 v31, v32
	s_waitcnt lgkmcnt(0)
	v_pk_mul_f32 v[30:31], v[54:55], v[30:31]
	s_nop 0
	v_sub_f32_e32 v30, v30, v31
.LBB0_365:
	s_or_b64 exec, exec, s[2:3]
	s_waitcnt lgkmcnt(0)
	v_cndmask_b32_e64 v32, v19, v11, s[48:49]
	v_mul_f32_e32 v31, v83, v82
	v_cndmask_b32_e64 v32, v32, v3, s[44:45]
	v_cndmask_b32_e64 v33, v20, v12, s[48:49]
	v_mul_f32_e32 v31, v32, v31
	v_mul_f32_e32 v32, v83, v61
	v_cndmask_b32_e64 v33, v33, v4, s[44:45]
	s_waitcnt lgkmcnt(0)
	v_cndmask_b32_e64 v54, v21, v13, s[48:49]
	v_mul_f32_e32 v32, v33, v32
	v_mul_f32_e32 v33, v83, v60
	v_cndmask_b32_e64 v54, v54, v5, s[44:45]
	v_cndmask_b32_e64 v55, v22, v14, s[48:49]
	v_mul_f32_e32 v33, v54, v33
	v_mul_f32_e32 v54, v83, v57
	v_cndmask_b32_e64 v55, v55, v6, s[44:45]
	v_mul_f32_e32 v54, v55, v54
	v_mul_f32_e32 v55, v83, v56
	v_cndmask_b32_e64 v56, v23, v15, s[48:49]
	v_cndmask_b32_e64 v56, v56, v7, s[44:45]
	v_cndmask_b32_e64 v57, v24, v16, s[48:49]
	v_mul_f32_e32 v55, v56, v55
	v_mul_f32_e32 v56, v83, v59
	v_cndmask_b32_e64 v57, v57, v8, s[44:45]
	v_mul_f32_e32 v56, v57, v56
	v_mul_f32_e32 v57, v83, v58
	v_cndmask_b32_e64 v58, v25, v17, s[48:49]
	v_cndmask_b32_e64 v58, v58, v9, s[44:45]
	v_mul_f32_e32 v57, v58, v57
	v_add_u32_e32 v58, 4, v27
	s_nop 1
	v_mov_b32_dpp v59, v31 quad_perm:[1,0,3,2] row_mask:0xf bank_mask:0xf
	ds_read2st64_b32 v[60:61], v58 offset1:8
	v_cmp_lt_i32_e64 s[48:49], 0, v62
	s_and_saveexec_b64 s[2:3], s[48:49]
	s_xor_b64 s[2:3], exec, s[2:3]
	s_cbranch_execz .LBB0_369
	v_cmp_eq_u32_e64 s[48:49], 1, v62
	s_and_saveexec_b64 s[8:9], s[48:49]
	s_cbranch_execz .LBB0_368
	v_mov_b32_e32 v58, v31
	s_waitcnt lgkmcnt(0)
	v_mul_f32_e32 v82, v31, v60
	v_pk_fma_f32 v[58:59], v[58:59], v[60:61], v[82:83] op_sel_hi:[1,1,0]
	s_nop 0
	v_mov_b32_e32 v31, v59

.LBB0_485:
	s_andn2_saveexec_b64 s[2:3], s[2:3]
	v_mov_b32_e32 v30, v26
	s_or_b64 exec, exec, s[2:3]
	v_add_u32_e32 v28, s12, v27
	v_mov_b64_e32 v[54:55], s[10:11]
	v_mad_i64_i32 v[54:55], s[2:3], v28, s23, v[54:55]
	v_ashrrev_i32_e32 v31, 31, v30
	v_lshl_add_u64 v[30:31], v[30:31], 1, v[54:55]
	v_lshl_add_u64 v[30:31], v[30:31], 0, v[0:1]
	global_load_dwordx4 v[56:59], v[30:31], off
	v_lshl_add_u32 v27, v27, 5, 0
	v_cmp_lt_i32_e64 s[50:51], 0, v62
	s_waitcnt vmcnt(0)
	v_and_b32_e32 v61, 0xffff0000, v56
	v_lshlrev_b32_e32 v29, 16, v56
	v_mul_f32_e32 v32, v61, v61
	v_lshlrev_b32_e32 v60, 16, v57
	v_fmac_f32_e32 v32, v29, v29
	v_and_b32_e32 v57, 0xffff0000, v57
	v_fmac_f32_e32 v32, v60, v60
	v_lshlrev_b32_e32 v56, 16, v58
	v_fmac_f32_e32 v32, v57, v57
	v_and_b32_e32 v53, 0xffff0000, v58
	v_and_b32_e32 v58, 0xffff0000, v59
	v_lshlrev_b32_e32 v59, 16, v59
	v_fmac_f32_e32 v32, v56, v56
	v_pk_mul_f32 v[30:31], v[58:59], v[58:59]
	v_fmac_f32_e32 v32, v53, v53
	v_add_f32_e32 v31, v31, v32
	v_add_f32_e32 v30, v30, v31
	s_nop 1
	v_mov_b32_dpp v31, v30 quad_perm:[1,0,3,2] row_mask:0xf bank_mask:0xf
	s_waitcnt lgkmcnt(0)
	v_add_f32_e32 v30, v30, v31
	s_nop 1
	v_mov_b32_dpp v31, v30 quad_perm:[2,3,0,1] row_mask:0xf bank_mask:0xf
	s_waitcnt lgkmcnt(0)
	v_add_f32_e32 v30, v30, v31
	s_nop 1
	v_mov_b32_dpp v31, v30 row_half_mirror row_mask:0xf bank_mask:0xf
	s_waitcnt lgkmcnt(0)
	v_add_f32_e32 v30, v30, v31
	v_fmamk_f32 v30, v30, 0x3c800000, v188
	v_mul_f32_e32 v31, 0x4f800000, v30
	v_cmp_gt_f32_e32 vcc, s66, v30
	s_nop 1
	v_cndmask_b32_e32 v30, v30, v31, vcc
	v_sqrt_f32_e32 v31, v30
	s_nop 0
	v_add_u32_e32 v32, -1, v31
	v_add_u32_e32 v54, 1, v31
	v_fma_f32 v55, -v32, v31, v30
	v_fma_f32 v82, -v54, v31, v30
	v_cmp_ge_f32_e64 s[48:49], 0, v55
	s_nop 1
	v_cndmask_b32_e64 v31, v31, v32, s[48:49]
	v_cmp_lt_f32_e64 s[48:49], 0, v82
	s_nop 1
	v_cndmask_b32_e64 v31, v31, v54, s[48:49]
	v_mul_f32_e32 v32, 0x37800000, v31
	v_cndmask_b32_e32 v31, v31, v32, vcc
	v_cmp_class_f32_e32 vcc, v30, v192
	v_cmp_gt_u32_e64 s[48:49], 10, v33
	s_nop 0
	v_cndmask_b32_e32 v30, v31, v30, vcc
	v_div_scale_f32 v31, s[2:3], v30, v30, 1.0
	v_rcp_f32_e32 v32, v31
	v_div_scale_f32 v55, vcc, 1.0, v30, 1.0
	v_cndmask_b32_e64 v54, v18, v10, s[48:49]
	v_fma_f32 v82, -v31, v32, 1.0
	v_fmac_f32_e32 v32, v82, v32
	v_mul_f32_e32 v82, v55, v32
	v_fma_f32 v83, -v31, v82, v55
	v_fmac_f32_e32 v82, v83, v32
	v_fma_f32 v31, -v31, v82, v55
	v_div_fmas_f32 v31, v31, v32, v82
	v_div_fixup_f32 v82, v31, v30, 1.0
	v_mul_f32_e32 v29, v82, v29
	v_cndmask_b32_e64 v30, v54, v2, s[44:45]
	v_mul_f32_e32 v30, v30, v29
	s_nop 1
	v_mov_b32_dpp v32, v30 quad_perm:[1,0,3,2] row_mask:0xf bank_mask:0xf
	ds_read2st64_b32 v[54:55], v27 offset1:8
	v_ashrrev_i32_e32 v29, 31, v28
	v_cmp_lt_u32_e32 vcc, 9, v33
	s_and_saveexec_b64 s[2:3], s[50:51]
	s_xor_b64 s[2:3], exec, s[2:3]
	s_cbranch_execz .LBB0_491
	v_cmp_eq_u32_e64 s[50:51], 1, v62
	s_and_saveexec_b64 s[8:9], s[50:51]
	s_cbranch_execz .LBB0_490
	s_waitcnt lgkmcnt(0)
	v_mov_b32_e32 v84, v55
	v_mov_b32_e32 v85, v54
	v_mov_b32_e32 v33, v30
	v_pk_mul_f32 v[30:31], v[84:85], v[32:33]
	s_nop 0
	v_add_f32_e32 v30, v30, v31

.LBB0_493:
	s_or_b64 exec, exec, s[2:3]
	s_waitcnt lgkmcnt(0)
	v_cndmask_b32_e64 v32, v19, v11, s[48:49]
	v_mul_f32_e32 v31, v82, v61
	v_cndmask_b32_e64 v32, v32, v3, s[44:45]
	v_cndmask_b32_e64 v33, v20, v12, s[48:49]
	v_mul_f32_e32 v31, v32, v31
	v_mul_f32_e32 v32, v82, v60
	v_cndmask_b32_e64 v33, v33, v4, s[44:45]
	s_waitcnt lgkmcnt(0)
	v_cndmask_b32_e64 v54, v21, v13, s[48:49]
	v_mul_f32_e32 v32, v33, v32
	v_mul_f32_e32 v33, v82, v57
	v_cndmask_b32_e64 v54, v54, v5, s[44:45]
	v_cndmask_b32_e64 v55, v22, v14, s[48:49]
	v_mul_f32_e32 v33, v54, v33
	v_mul_f32_e32 v54, v82, v56
	v_cndmask_b32_e64 v55, v55, v6, s[44:45]
	v_mul_f32_e32 v54, v55, v54
	v_cndmask_b32_e64 v55, v23, v15, s[48:49]
	v_mul_f32_e32 v53, v82, v53
	v_cndmask_b32_e64 v55, v55, v7, s[44:45]
	v_cndmask_b32_e64 v56, v24, v16, s[48:49]
	v_mul_f32_e32 v55, v55, v53
	v_mul_f32_e32 v53, v82, v59
	v_cndmask_b32_e64 v56, v56, v8, s[44:45]
	v_cndmask_b32_e64 v57, v25, v17, s[48:49]
	v_mul_f32_e32 v56, v56, v53
	v_mul_f32_e32 v53, v82, v58
	v_cndmask_b32_e64 v57, v57, v9, s[44:45]
	v_mul_f32_e32 v57, v57, v53
	v_add_u32_e32 v53, 4, v27
	s_nop 1
	v_mov_b32_dpp v59, v31 quad_perm:[1,0,3,2] row_mask:0xf bank_mask:0xf
	ds_read2st64_b32 v[60:61], v53 offset1:8
	v_cmp_lt_i32_e64 s[48:49], 0, v62
	s_and_saveexec_b64 s[2:3], s[48:49]
	s_xor_b64 s[2:3], exec, s[2:3]
	s_cbranch_execz .LBB0_497
	v_cmp_eq_u32_e64 s[48:49], 1, v62
	s_and_saveexec_b64 s[8:9], s[48:49]
	s_cbranch_execz .LBB0_496
	v_mov_b32_e32 v58, v31
	s_waitcnt lgkmcnt(0)
	v_mul_f32_e32 v82, v31, v60
	v_pk_fma_f32 v[58:59], v[58:59], v[60:61], v[82:83] op_sel_hi:[1,1,0]
	s_nop 0
	v_mov_b32_e32 v31, v59

.LBB0_499:
	s_or_b64 exec, exec, s[2:3]
	v_add_u32_e32 v53, 8, v27
	s_waitcnt lgkmcnt(0)
	s_nop 1
	v_mov_b32_dpp v59, v32 quad_perm:[1,0,3,2] row_mask:0xf bank_mask:0xf
	s_waitcnt lgkmcnt(0)
	ds_read2st64_b32 v[60:61], v53 offset1:8
	v_cmp_lt_i32_e64 s[48:49], 0, v62
	s_and_saveexec_b64 s[2:3], s[48:49]
	s_xor_b64 s[2:3], exec, s[2:3]
	s_cbranch_execz .LBB0_503
	v_cmp_eq_u32_e64 s[48:49], 1, v62
	s_and_saveexec_b64 s[8:9], s[48:49]
	s_cbranch_execz .LBB0_502
	v_mov_b32_e32 v58, v32
	s_waitcnt lgkmcnt(0)
	v_mul_f32_e32 v32, v59, v61
	v_pk_fma_f32 v[58:59], v[58:59], v[60:61], v[32:33] op_sel_hi:[1,1,0]
	s_nop 0
	v_mov_b32_e32 v32, v58

.LBB0_505:
	s_or_b64 exec, exec, s[2:3]
	v_add_u32_e32 v53, 12, v27
	s_waitcnt lgkmcnt(0)
	s_nop 1
	v_mov_b32_dpp v59, v33 quad_perm:[1,0,3,2] row_mask:0xf bank_mask:0xf
	s_waitcnt lgkmcnt(0)
	ds_read2st64_b32 v[60:61], v53 offset1:8
	v_cmp_lt_i32_e64 s[48:49], 0, v62
	s_and_saveexec_b64 s[2:3], s[48:49]
	s_xor_b64 s[2:3], exec, s[2:3]
	s_cbranch_execz .LBB0_509
	v_cmp_eq_u32_e64 s[48:49], 1, v62
	s_and_saveexec_b64 s[8:9], s[48:49]
	s_cbranch_execz .LBB0_508
	v_mov_b32_e32 v58, v33
	s_waitcnt lgkmcnt(0)
	v_mul_f32_e32 v82, v59, v61
	v_pk_fma_f32 v[58:59], v[58:59], v[60:61], v[82:83] op_sel_hi:[1,1,0]
	s_nop 0
	v_mov_b32_e32 v33, v58

.LBB0_511:
	s_or_b64 exec, exec, s[2:3]
	v_add_u32_e32 v53, 16, v27
	s_waitcnt lgkmcnt(0)
	s_nop 1
	v_mov_b32_dpp v59, v54 quad_perm:[1,0,3,2] row_mask:0xf bank_mask:0xf
	s_waitcnt lgkmcnt(0)
	ds_read2st64_b32 v[60:61], v53 offset1:8
	v_cmp_lt_i32_e64 s[48:49], 0, v62
	s_and_saveexec_b64 s[2:3], s[48:49]
	s_xor_b64 s[2:3], exec, s[2:3]
	s_cbranch_execz .LBB0_515
	v_cmp_eq_u32_e64 s[48:49], 1, v62
	s_and_saveexec_b64 s[8:9], s[48:49]
	s_cbranch_execz .LBB0_514
	v_mov_b32_e32 v58, v54
	s_waitcnt lgkmcnt(0)
	v_mul_f32_e32 v54, v59, v61
	v_pk_fma_f32 v[58:59], v[58:59], v[60:61], v[54:55] op_sel_hi:[1,1,0]
	s_nop 0
	v_mov_b32_e32 v54, v58

.LBB0_517:
	s_or_b64 exec, exec, s[2:3]
	v_add_u32_e32 v53, 20, v27
	s_waitcnt lgkmcnt(0)
	s_nop 1
	v_mov_b32_dpp v59, v55 quad_perm:[1,0,3,2] row_mask:0xf bank_mask:0xf
	s_waitcnt lgkmcnt(0)
	ds_read2st64_b32 v[60:61], v53 offset1:8
	v_cmp_lt_i32_e64 s[48:49], 0, v62
	s_and_saveexec_b64 s[2:3], s[48:49]
	s_xor_b64 s[2:3], exec, s[2:3]
	s_cbranch_execz .LBB0_521
	v_cmp_eq_u32_e64 s[48:49], 1, v62
	s_and_saveexec_b64 s[8:9], s[48:49]
	s_cbranch_execz .LBB0_520
	v_mov_b32_e32 v58, v55
	s_waitcnt lgkmcnt(0)
	v_mul_f32_e32 v82, v59, v61
	v_pk_fma_f32 v[58:59], v[58:59], v[60:61], v[82:83] op_sel_hi:[1,1,0]
	s_nop 0
	v_mov_b32_e32 v55, v58

.LBB0_523:
	s_or_b64 exec, exec, s[2:3]
	v_add_u32_e32 v53, 24, v27
	s_waitcnt lgkmcnt(0)
	s_nop 1
	v_mov_b32_dpp v59, v56 quad_perm:[1,0,3,2] row_mask:0xf bank_mask:0xf
	s_waitcnt lgkmcnt(0)
	ds_read2st64_b32 v[60:61], v53 offset1:8
	v_cmp_lt_i32_e64 s[48:49], 0, v62
	s_and_saveexec_b64 s[2:3], s[48:49]
	s_xor_b64 s[2:3], exec, s[2:3]
	s_cbranch_execz .LBB0_527
	v_cmp_eq_u32_e64 s[48:49], 1, v62
	s_and_saveexec_b64 s[8:9], s[48:49]
	s_cbranch_execz .LBB0_526
	v_mov_b32_e32 v58, v56
	s_waitcnt lgkmcnt(0)
	v_mul_f32_e32 v56, v59, v61
	v_pk_fma_f32 v[58:59], v[58:59], v[60:61], v[56:57] op_sel_hi:[1,1,0]
	s_nop 0
	v_mov_b32_e32 v56, v58

.LBB0_542:
	v_lshlrev_b64 v[28:29], 10, v[28:29]
	v_lshl_add_u64 v[28:29], s[86:87], 0, v[28:29]
	v_ashrrev_i32_e32 v27, 31, v26
	s_waitcnt lgkmcnt(0)
	v_lshl_add_u64 v[58:59], v[26:27], 1, v[28:29]
	s_branch .LBB0_286
